# best version plus one static s_setprio 1 for waves 4-7 during the attention phase (reset at phase exit)
# baseline (speedup 1.0000x reference)
; #define LAS __attribute__((address_space(3)))
; #define SEAM(k) do { if (IN(k) && IN((k) + 1)) xcd_barrier(bar); } while (0)
; __device__ __forceinline__ void shw_phase(LAS unsigned char* lds, const float* mod, int sh_idx, const bf16* Wt, int N, float* shw) {
;     const int tid = threadIdx.x, lane = tid & 63, wave = __builtin_amdgcn_readfirstlane(tid >> 6);
;     LAS float* sh = (LAS float*)lds;
;     __syncthreads();
;     for (int i = tid; i < 8 * D / 4; i += NTHREADS) { const int r = i / (D / 4), c = (i % (D / 4)) * 4; *(LAS f32x4*)(sh + r * D + c) = *(const f32x4*)(mod + (size_t)r * NMOD + (size_t)sh_idx * D + c); }
;     __syncthreads();
; __global__ void __launch_bounds__(NTHREADS, 2) fwd_megakernel(Args args) {
;     ...
;     if (IN(10)) { shw_phase(lds, MOD1, 3, (const bf16*)(ws + WS_W1) + W1_STRIDE, FF, SHWC); att::attn_phase(lds, QKb, VTb, Ob, args.in[12]); } SEAM(10);
.LBB0_917:
	s_cmp_lt_i32 s26, 11
	s_cselect_b64 s[4:5], -1, 0
	s_add_u32 s72, s24, 0x2f063000
	s_addc_u32 s73, s25, 0
	s_add_u32 s40, s24, 0x1f900000
	s_addc_u32 s41, s25, 0
	s_and_b64 s[42:43], s[4:5], s[0:1]
	s_andn2_b64 vcc, exec, s[42:43]
	s_cbranch_vccnz .LBB0_981
	v_readfirstlane_b32 s98, v146
	s_cmpk_lt_u32 s98, 0x100
	s_cbranch_scc1 .Lattn_noprio
	s_setprio 1
.Lattn_noprio:
	v_lshrrev_b32_e32 v38, 9, v146
	s_add_u32 s0, s24, 0x72000
	v_mul_u32_u24_e32 v0, 0x3000, v38
	s_addc_u32 s1, s25, 0
	v_lshlrev_b32_e32 v0, 2, v0
	s_waitcnt lgkmcnt(0)
	v_mov_b32_e32 v1, 0
	v_lshlrev_b32_e32 v18, 4, v146
	v_add_u32_e32 v19, 0x200, v146
	v_lshl_add_u64 v[2:3], s[0:1], 0, v[0:1]
	v_and_b32_e32 v0, 0x1ff0, v18
	v_lshrrev_b32_e32 v39, 9, v19
	v_lshl_add_u64 v[20:21], v[2:3], 0, v[0:1]
	v_mul_u32_u24_e32 v2, 0x3000, v39
	v_lshlrev_b32_e32 v2, 2, v2
	v_mov_b32_e32 v3, v1
	v_lshlrev_b32_e32 v4, 4, v19
	v_lshl_add_u64 v[2:3], s[0:1], 0, v[2:3]
	v_and_b32_e32 v32, 0x1ff0, v4
	v_mov_b32_e32 v33, v1
	v_add_u32_e32 v12, 0x600, v146
	v_lshl_add_u64 v[10:11], v[2:3], 0, v[32:33]
	v_lshrrev_b32_e32 v33, 9, v12
	s_waitcnt vmcnt(0)
	s_barrier
	global_load_dwordx4 v[2:5], v[20:21], off
	global_load_dwordx4 v[6:9], v[10:11], off
	s_mov_b32 s3, 0x18000
	v_mul_u32_u24_e32 v10, 0x3000, v33
	v_add_co_u32_e32 v22, vcc, s3, v20
	v_lshlrev_b32_e32 v10, 2, v10
	v_mov_b32_e32 v11, v1
	v_lshlrev_b32_e32 v12, 4, v12
	v_addc_co_u32_e32 v23, vcc, 0, v21, vcc
	v_lshl_add_u64 v[10:11], s[0:1], 0, v[10:11]
	v_and_b32_e32 v34, 0x1ff0, v12
	v_mov_b32_e32 v35, v1
	v_lshl_add_u64 v[24:25], v[10:11], 0, v[34:35]
	global_load_dwordx4 v[10:13], v[22:23], off
	global_load_dwordx4 v[14:17], v[24:25], off
	v_add_u32_e32 v22, 0xa00, v146
	s_mov_b32 s3, 0x30000
	v_lshrrev_b32_e32 v35, 9, v22
	v_add_co_u32_e32 v28, vcc, s3, v20
	v_mul_u32_u24_e32 v20, 0x3000, v35
	s_nop 0
	v_addc_co_u32_e32 v29, vcc, 0, v21, vcc
	v_lshlrev_b32_e32 v20, 2, v20
	v_mov_b32_e32 v21, v1
	v_lshlrev_b32_e32 v22, 4, v22
	v_lshl_add_u64 v[20:21], s[0:1], 0, v[20:21]
	v_and_b32_e32 v36, 0x1ff0, v22
	v_mov_b32_e32 v37, v1
	v_lshl_add_u64 v[30:31], v[20:21], 0, v[36:37]
	global_load_dwordx4 v[20:23], v[28:29], off
	global_load_dwordx4 v[24:27], v[30:31], off
	v_or_b32_e32 v37, 0xc00, v146
	v_lshrrev_b32_e32 v40, 9, v37
	v_mul_u32_u24_e32 v28, 0x3000, v40
	v_lshlrev_b32_e32 v28, 2, v28
	v_mov_b32_e32 v29, v1
	v_lshl_add_u64 v[28:29], s[0:1], 0, v[28:29]
	v_lshl_add_u64 v[28:29], v[28:29], 0, v[0:1]
	global_load_dwordx4 v[28:31], v[28:29], off
	s_movk_i32 s3, 0xe00
	v_lshlrev_b32_e32 v38, 13, v38
	v_lshlrev_b32_e32 v33, 13, v33
	v_lshlrev_b32_e32 v35, 13, v35
	v_lshlrev_b32_e32 v39, 13, v39
	v_lshlrev_b32_e32 v40, 13, v40
	v_add3_u32 v33, 0, v33, v34
	v_add3_u32 v34, 0, v35, v36
	v_add3_u32 v35, 0, v38, v0
	v_cmp_gt_u32_e32 vcc, s3, v37
	v_add3_u32 v32, 0, v39, v32
	v_add3_u32 v0, 0, v40, v0
	s_waitcnt vmcnt(6)
	ds_write_b128 v35, v[2:5]
	s_waitcnt vmcnt(5)
	ds_write_b128 v32, v[6:9]
	s_waitcnt vmcnt(4)
	ds_write_b128 v35, v[10:13] offset:16384
	s_waitcnt vmcnt(3)
	ds_write_b128 v33, v[14:17]
	s_waitcnt vmcnt(2)
	ds_write_b128 v35, v[20:23] offset:32768
	s_waitcnt vmcnt(1)
	ds_write_b128 v34, v[24:27]
	s_waitcnt vmcnt(0)
	ds_write_b128 v0, v[28:31]
	s_and_saveexec_b64 s[4:5], vcc
	s_cbranch_execz .LBB0_920
	v_add_u32_e32 v4, 0xe00, v146
	v_lshrrev_b32_e32 v6, 9, v4
	v_mul_u32_u24_e32 v0, 0x3000, v6
	v_lshlrev_b32_e32 v0, 2, v0
	v_lshl_add_u64 v[2:3], s[0:1], 0, v[0:1]
	v_lshlrev_b32_e32 v0, 4, v4
	v_and_b32_e32 v0, 0x1ff0, v0
	v_lshl_add_u64 v[2:3], v[2:3], 0, v[0:1]
	global_load_dwordx4 v[2:5], v[2:3], off
	v_lshlrev_b32_e32 v1, 13, v6
	v_add3_u32 v0, 0, v1, v0
	s_waitcnt vmcnt(0)
	ds_write_b128 v0, v[2:5]

; __device__ __forceinline__ unsigned xb_ld(unsigned* p)              { return __hip_atomic_load(p, __ATOMIC_RELAXED, __HIP_MEMORY_SCOPE_AGENT); }
; __device__ __forceinline__ void xcd_barrier_complete(unsigned* bar, unsigned x, unsigned& nloc, unsigned& nx) {
;     const unsigned G = gridDim.x * gridDim.y * gridDim.z;
;     unsigned sum, cnt, mine, sp = 0u;
;     for (;;) {
;         sum = 0u; cnt = 0u; mine = 0u;
; #pragma unroll
;         for (unsigned j = 0; j < 16; ++j) { const unsigned c = xb_ld(&bar[XB_XCNT(j)]); sum += c; cnt += (c > 0u) ? 1u : 0u; mine = (j == x) ? c : mine; }
; __device__ __forceinline__ void xcd_barrier(const XcdBarrier& b) {
;     asm volatile("s_waitcnt vmcnt(0)" ::: "memory");
;     __syncthreads();
;     if (threadIdx.x == 0) {
;         unsigned* bar = b.bar;
;         __builtin_amdgcn_s_waitcnt(0);
;         unsigned nloc = b.st[0], nx = b.st[1];
;         if (nloc == 0u) { xcd_barrier_complete(bar, b.x, nloc, nx); b.st[0] = nloc; b.st[1] = nx; }
.LBB0_981:
	s_setprio 0
	s_cmp_gt_i32 s27, 11
	s_cselect_b64 s[0:1], -1, 0
	s_and_b64 s[4:5], s[42:43], s[0:1]
	s_andn2_b64 vcc, exec, s[4:5]
	s_cbranch_vccnz .LBB0_1031
	s_waitcnt vmcnt(0)
	v_cmp_eq_u32_e32 vcc, 0, v146
	s_waitcnt vmcnt(0) lgkmcnt(0)
	s_barrier
	s_and_saveexec_b64 s[4:5], vcc
	s_cbranch_execz .LBB0_1030
	s_add_i32 s3, 0, 0x20020
	v_mov_b32_e32 v0, s3
	s_waitcnt vmcnt(0) expcnt(0) lgkmcnt(0)
	ds_read_b32 v2, v0
	s_add_i32 s3, 0, 0x20024
	v_mov_b32_e32 v0, s3
	ds_read_b32 v0, v0
	s_waitcnt lgkmcnt(1)
	v_cmp_ne_u32_e32 vcc, 0, v2
	s_cbranch_vccnz .LBB0_998
	s_add_u32 s6, s24, 0xdc200
	s_addc_u32 s7, s25, 0
	s_add_u32 s8, s24, 0xdc400
	s_addc_u32 s9, s25, 0
	s_add_u32 s10, s24, 0xdc500
	s_addc_u32 s11, s25, 0
	s_add_u32 s12, s24, 0xdc600
	s_addc_u32 s13, s25, 0
	s_add_u32 s14, s24, 0xdc700
	s_addc_u32 s15, s25, 0
	s_add_u32 s36, s24, 0xdc800
	s_addc_u32 s37, s25, 0
	s_add_u32 s42, s24, 0xdc900
	s_addc_u32 s43, s25, 0
	s_add_u32 s44, s24, 0xdca00
	s_addc_u32 s45, s25, 0
	s_add_u32 s48, s24, 0xdcb00
	s_addc_u32 s49, s25, 0
	s_add_u32 s50, s24, 0xdcc00
	s_addc_u32 s51, s25, 0
	s_add_u32 s52, s24, 0xdcd00
	s_addc_u32 s53, s25, 0
	s_add_u32 s54, s24, 0xdce00
	s_addc_u32 s55, s25, 0
	s_add_u32 s56, s24, 0xdcf00
	s_addc_u32 s57, s25, 0
	s_add_u32 s58, s24, 0xdd000
	s_addc_u32 s59, s25, 0
	s_add_u32 s60, s24, 0xdd100
	s_addc_u32 s61, s25, 0
	s_add_u32 s62, s24, 0xdd200
	v_readlane_b32 s3, v252, 16
	s_addc_u32 s63, s25, 0
	s_mul_i32 s3, s19, s3
	s_add_u32 s64, s24, 0xdd300
	s_mul_i32 s3, s3, s18
	s_addc_u32 s65, s25, 0
	s_mov_b32 s28, 1
	v_mov_b32_e32 v16, 0
	s_branch .LBB0_986

; __global__ void __launch_bounds__(NTHREADS, 2) fwd_megakernel(Args args) {
	.amdhsa_kernel _Z14fwd_megakernel4Args
		.amdhsa_group_segment_fixed_size 0
		.amdhsa_private_segment_fixed_size 0
		.amdhsa_kernarg_size 416
		.amdhsa_user_sgpr_count 2
		.amdhsa_user_sgpr_dispatch_ptr 0
		.amdhsa_user_sgpr_queue_ptr 0
		.amdhsa_user_sgpr_kernarg_segment_ptr 1
		.amdhsa_user_sgpr_dispatch_id 0
		.amdhsa_user_sgpr_kernarg_preload_length 0
		.amdhsa_user_sgpr_kernarg_preload_offset 0
		.amdhsa_user_sgpr_private_segment_size 0
		.amdhsa_uses_dynamic_stack 0
		.amdhsa_enable_private_segment 0
		.amdhsa_system_sgpr_workgroup_id_x 1
		.amdhsa_system_sgpr_workgroup_id_y 0
		.amdhsa_system_sgpr_workgroup_id_z 0
		.amdhsa_system_sgpr_workgroup_info 0
		.amdhsa_system_vgpr_workitem_id 2
		.amdhsa_next_free_vgpr 256
		.amdhsa_next_free_sgpr 100
		.amdhsa_accum_offset 256
		.amdhsa_reserve_vcc 1
		.amdhsa_float_round_mode_32 0
		.amdhsa_float_round_mode_16_64 0
		.amdhsa_float_denorm_mode_32 3
		.amdhsa_float_denorm_mode_16_64 3
		.amdhsa_dx10_clamp 1
		.amdhsa_ieee_mode 1
		.amdhsa_fp16_overflow 0
		.amdhsa_tg_split 0
		.amdhsa_exception_fp_ieee_invalid_op 0
		.amdhsa_exception_fp_denorm_src 0
		.amdhsa_exception_fp_ieee_div_zero 0
		.amdhsa_exception_fp_ieee_overflow 0
		.amdhsa_exception_fp_ieee_underflow 0
		.amdhsa_exception_fp_ieee_inexact 0
		.amdhsa_exception_int_div_zero 0
	.end_amdhsa_kernel

; __global__ void __launch_bounds__(NTHREADS, 2) fwd_megakernel(Args args) {
amdhsa.kernels:
  - .agpr_count:     0
    .args:
      - .offset:         0
        .size:           160
        .value_kind:     by_value
      - .offset:         160
        .size:           4
        .value_kind:     hidden_block_count_x
      - .offset:         164
        .size:           4
        .value_kind:     hidden_block_count_y
      - .offset:         168
        .size:           4
        .value_kind:     hidden_block_count_z
      - .offset:         172
        .size:           2
        .value_kind:     hidden_group_size_x
      - .offset:         174
        .size:           2
        .value_kind:     hidden_group_size_y
      - .offset:         176
        .size:           2
        .value_kind:     hidden_group_size_z
      - .offset:         178
        .size:           2
        .value_kind:     hidden_remainder_x
      - .offset:         180
        .size:           2
        .value_kind:     hidden_remainder_y
      - .offset:         182
        .size:           2
        .value_kind:     hidden_remainder_z
      - .offset:         200
        .size:           8
        .value_kind:     hidden_global_offset_x
      - .offset:         208
        .size:           8
        .value_kind:     hidden_global_offset_y
      - .offset:         216
        .size:           8
        .value_kind:     hidden_global_offset_z
      - .offset:         224
        .size:           2
        .value_kind:     hidden_grid_dims
      - .offset:         248
        .size:           8
        .value_kind:     hidden_multigrid_sync_arg
      - .offset:         280
        .size:           4
        .value_kind:     hidden_dynamic_lds_size
    .group_segment_fixed_size: 0
    .kernarg_segment_align: 8
    .kernarg_segment_size: 416
    .language:       OpenCL C
    .language_version:
      - 2
      - 0
    .max_flat_workgroup_size: 512
    .name:           _Z14fwd_megakernel4Args
    .private_segment_fixed_size: 0
    .sgpr_count:     106
    .sgpr_spill_count: 19
    .symbol:         _Z14fwd_megakernel4Args.kd
    .uniform_work_group_size: 1
    .uses_dynamic_stack: false
    .vgpr_count:     256
    .vgpr_spill_count: 0
    .wavefront_size: 64
